# out-proj epilogue: five of the second row-half residual loads issued together with the first half (into dead K-loop fragment registers), hiding one memory latency per tile
# speedup vs baseline: 1.0024x; 1.0024x over previous
.LBB0_558:
	s_lshl_b32 s28, s20, 8
	s_or_b32 s27, s28, s83
	v_lshl_add_u32 v172, s26, 8, v184
	s_ashr_i32 s29, s28, 31
	s_lshr_b64 s[28:29], s[28:29], 10
	v_bitop3_b32 v120, s27, 56, v185 bitop3:0xc8
	s_ashr_i32 s34, s27, 6
	v_ashrrev_i32_e32 v173, 31, v172
	v_lshlrev_b32_e32 v220, 1, v120
	s_ashr_i32 s35, s34, 31
	v_lshl_add_u64 v[120:121], s[28:29], 0, v[172:173]
	s_lshl_b64 s[62:63], s[34:35], 21
	v_lshlrev_b64 v[120:121], 7, v[120:121]
	s_or_b32 s34, s34, 2
	v_lshl_add_u64 v[170:171], s[8:9], 0, v[220:221]
	v_and_b32_e32 v121, 0x1fffffff, v121
	v_and_b32_e32 v120, 0xffffff80, v120
	s_ashr_i32 s35, s34, 31
	v_lshl_add_u64 v[120:121], v[170:171], 0, v[120:121]
	s_lshl_b64 s[60:61], s[34:35], 21
	v_or_b32_e32 v178, 16, v172
	v_lshl_add_u64 v[122:123], v[120:121], 0, s[62:63]
	v_lshl_add_u64 v[120:121], v[120:121], 0, s[60:61]
	v_ashrrev_i32_e32 v179, 31, v178
	global_load_dwordx4 v[188:191], v[122:123], off
	global_load_dwordx4 v[152:155], v[120:121], off
	v_lshl_add_u64 v[120:121], s[28:29], 0, v[178:179]
	v_lshlrev_b64 v[120:121], 7, v[120:121]
	v_and_b32_e32 v121, 0x1fffffff, v121
	v_and_b32_e32 v120, 0xffffff80, v120
	v_lshl_add_u64 v[120:121], v[170:171], 0, v[120:121]
	v_or_b32_e32 v176, 32, v172
	v_lshl_add_u64 v[122:123], v[120:121], 0, s[62:63]
	v_lshl_add_u64 v[120:121], v[120:121], 0, s[60:61]
	v_ashrrev_i32_e32 v177, 31, v176
	global_load_dwordx4 v[148:151], v[122:123], off
	global_load_dwordx4 v[144:147], v[120:121], off
	v_lshl_add_u64 v[120:121], s[28:29], 0, v[176:177]
	v_lshlrev_b64 v[120:121], 7, v[120:121]
	v_and_b32_e32 v121, 0x1fffffff, v121
	v_and_b32_e32 v120, 0xffffff80, v120
	v_lshl_add_u64 v[120:121], v[170:171], 0, v[120:121]
	v_or_b32_e32 v174, 48, v172
	v_lshl_add_u64 v[122:123], v[120:121], 0, s[62:63]
	v_lshl_add_u64 v[120:121], v[120:121], 0, s[60:61]
	v_ashrrev_i32_e32 v175, 31, v174
	global_load_dwordx4 v[140:143], v[122:123], off
	global_load_dwordx4 v[136:139], v[120:121], off
	v_lshl_add_u64 v[120:121], s[28:29], 0, v[174:175]
	v_lshlrev_b64 v[120:121], 7, v[120:121]
	v_and_b32_e32 v121, 0x1fffffff, v121
	v_and_b32_e32 v120, 0xffffff80, v120
	v_lshl_add_u64 v[120:121], v[170:171], 0, v[120:121]
	v_lshl_add_u64 v[122:123], v[120:121], 0, s[62:63]
	v_lshl_add_u64 v[120:121], v[120:121], 0, s[60:61]
	global_load_dwordx4 v[124:127], v[122:123], off
	v_lshlrev_b64 v[180:181], 7, v[172:173]
	global_load_dwordx4 v[120:123], v[120:121], off
	v_add_u32_e32 v186, 0x80, v172
	v_ashrrev_i32_e32 v187, 31, v186
	v_lshl_add_u64 v[186:187], s[28:29], 0, v[186:187]
	v_lshlrev_b64 v[186:187], 7, v[186:187]
	v_and_b32_e32 v187, 0x1fffffff, v187
	v_and_b32_e32 v186, 0xffffff80, v186
	v_lshl_add_u64 v[186:187], v[170:171], 0, v[186:187]
	v_lshl_add_u64 v[194:195], v[186:187], 0, s[62:63]
	global_load_dwordx4 v[194:197], v[194:195], off
	v_lshl_add_u64 v[198:199], v[186:187], 0, s[60:61]
	global_load_dwordx4 v[198:201], v[198:199], off
	v_add_u32_e32 v186, 0x90, v172
	v_ashrrev_i32_e32 v187, 31, v186
	v_lshl_add_u64 v[186:187], s[28:29], 0, v[186:187]
	v_lshlrev_b64 v[186:187], 7, v[186:187]
	v_and_b32_e32 v187, 0x1fffffff, v187
	v_and_b32_e32 v186, 0xffffff80, v186
	v_lshl_add_u64 v[186:187], v[170:171], 0, v[186:187]
	v_lshl_add_u64 v[202:203], v[186:187], 0, s[62:63]
	global_load_dwordx4 v[202:205], v[202:203], off
	v_lshl_add_u64 v[206:207], v[186:187], 0, s[60:61]
	global_load_dwordx4 v[206:209], v[206:207], off
	v_add_u32_e32 v186, 0xa0, v172
	v_ashrrev_i32_e32 v187, 31, v186
	v_lshl_add_u64 v[186:187], s[28:29], 0, v[186:187]
	v_lshlrev_b64 v[186:187], 7, v[186:187]
	v_and_b32_e32 v187, 0x1fffffff, v187
	v_and_b32_e32 v186, 0xffffff80, v186
	v_lshl_add_u64 v[186:187], v[170:171], 0, v[186:187]
	v_lshl_add_u64 v[210:211], v[186:187], 0, s[62:63]
	global_load_dwordx4 v[210:213], v[210:211], off
	s_mov_b64 s[34:35], -1
	s_and_b64 vcc, exec, s[44:45]
	s_waitcnt vmcnt(0)
	v_lshlrev_b32_e32 v168, 16, v188
	v_and_b32_e32 v169, 0xffff0000, v188
	v_lshlrev_b32_e32 v182, 16, v189
	v_and_b32_e32 v183, 0xffff0000, v189
	v_lshlrev_b32_e32 v188, 16, v190
	v_and_b32_e32 v189, 0xffff0000, v190
	v_lshlrev_b32_e32 v190, 16, v191
	v_and_b32_e32 v191, 0xffff0000, v191
	v_pk_add_f32 v[134:135], v[134:135], v[182:183]
	v_pk_add_f32 v[132:133], v[132:133], v[168:169]
	v_pk_add_f32 v[130:131], v[130:131], v[190:191]
	v_pk_add_f32 v[128:129], v[128:129], v[188:189]
	s_cbranch_vccz .LBB0_560
	v_pk_mul_f32 v[182:183], v[132:133], v[132:133]
	v_pk_mul_f32 v[190:191], v[128:129], v[128:129]
	v_pk_mul_f32 v[168:169], v[134:135], v[134:135]
	v_pk_mul_f32 v[188:189], v[130:131], v[130:131]
	v_mov_b32_e32 v192, v182
	v_mov_b32_e32 v193, v190
	v_mov_b32_e32 v190, v183
	v_pk_add_f32 v[182:183], v[192:193], v[190:191]
	v_mov_b32_e32 v190, v168
	v_mov_b32_e32 v191, v188
	v_mov_b32_e32 v188, v169
	v_pk_add_f32 v[168:169], v[190:191], v[188:189]
	s_add_u32 s34, s8, s62
	v_pk_add_f32 v[168:169], v[182:183], v[168:169]
	s_addc_u32 s35, s9, s63
	v_add_f32_e32 v188, v168, v169
	v_lshl_add_u64 v[168:169], s[34:35], 0, v[180:181]
	v_lshl_add_u64 v[168:169], v[168:169], 0, v[220:221]
	v_cvt_pk_bf16_f32 v190, v132, v133
	v_cvt_pk_bf16_f32 v191, v134, v135
	v_cvt_pk_bf16_f32 v192, v128, v129
	v_cvt_pk_bf16_f32 v193, v130, v131
	global_store_dwordx4 v[168:169], v[190:193], off
	s_mov_b64 s[34:35], 0

.LBB0_606:
	v_add_u32_e32 v98, 0x80, v172
	v_ashrrev_i32_e32 v99, 31, v98
	s_waitcnt lgkmcnt(0)
	v_lshl_add_u64 v[64:65], s[28:29], 0, v[98:99]
	v_lshlrev_b64 v[64:65], 7, v[64:65]
	v_and_b32_e32 v65, 0x1fffffff, v65
	v_and_b32_e32 v64, 0xffffff80, v64
	v_lshl_add_u64 v[64:65], v[170:171], 0, v[64:65]
	v_add_u32_e32 v96, 0x90, v172
	v_lshl_add_u64 v[66:67], v[64:65], 0, s[62:63]
	v_lshl_add_u64 v[64:65], v[64:65], 0, s[60:61]
	v_ashrrev_i32_e32 v97, 31, v96
	v_lshl_add_u64 v[64:65], s[28:29], 0, v[96:97]
	v_lshlrev_b64 v[64:65], 7, v[64:65]
	v_and_b32_e32 v65, 0x1fffffff, v65
	v_and_b32_e32 v64, 0xffffff80, v64
	v_lshl_add_u64 v[64:65], v[170:171], 0, v[64:65]
	v_add_u32_e32 v94, 0xa0, v172
	v_lshl_add_u64 v[66:67], v[64:65], 0, s[62:63]
	v_lshl_add_u64 v[64:65], v[64:65], 0, s[60:61]
	v_ashrrev_i32_e32 v95, 31, v94
	v_lshl_add_u64 v[64:65], s[28:29], 0, v[94:95]
	v_lshlrev_b64 v[64:65], 7, v[64:65]
	v_and_b32_e32 v65, 0x1fffffff, v65
	v_and_b32_e32 v64, 0xffffff80, v64
	v_lshl_add_u64 v[64:65], v[170:171], 0, v[64:65]
	v_add_u32_e32 v92, 0xb0, v172
	v_lshl_add_u64 v[66:67], v[64:65], 0, s[62:63]
	v_lshl_add_u64 v[64:65], v[64:65], 0, s[60:61]
	v_ashrrev_i32_e32 v93, 31, v92
	global_load_dwordx4 v[72:75], v[64:65], off
	v_lshl_add_u64 v[64:65], s[28:29], 0, v[92:93]
	v_lshlrev_b64 v[64:65], 7, v[64:65]
	v_and_b32_e32 v65, 0x1fffffff, v65
	v_and_b32_e32 v64, 0xffffff80, v64
	v_lshl_add_u64 v[64:65], v[170:171], 0, v[64:65]
	v_lshl_add_u64 v[66:67], v[64:65], 0, s[62:63]
	v_lshl_add_u64 v[64:65], v[64:65], 0, s[60:61]
	global_load_dwordx4 v[68:71], v[66:67], off
	v_lshlrev_b64 v[100:101], 7, v[98:99]
	global_load_dwordx4 v[64:67], v[64:65], off
	s_mov_b64 s[28:29], -1
	s_and_b64 vcc, exec, s[44:45]
	s_waitcnt vmcnt(7)
	v_lshlrev_b32_e32 v106, 16, v194
	v_and_b32_e32 v107, 0xffff0000, v194
	v_lshlrev_b32_e32 v102, 16, v195
	v_and_b32_e32 v103, 0xffff0000, v195
	v_lshlrev_b32_e32 v108, 16, v196
	v_and_b32_e32 v109, 0xffff0000, v196
	v_lshlrev_b32_e32 v104, 16, v197
	v_and_b32_e32 v105, 0xffff0000, v197
	v_pk_add_f32 v[62:63], v[62:63], v[102:103]
	v_pk_add_f32 v[60:61], v[60:61], v[106:107]
	v_pk_add_f32 v[58:59], v[58:59], v[104:105]
	v_pk_add_f32 v[56:57], v[56:57], v[108:109]
	s_cbranch_vccz .LBB0_608
	v_pk_mul_f32 v[104:105], v[60:61], v[60:61]
	v_pk_mul_f32 v[108:109], v[56:57], v[56:57]
	v_pk_mul_f32 v[102:103], v[62:63], v[62:63]
	v_pk_mul_f32 v[106:107], v[58:59], v[58:59]
	v_mov_b32_e32 v110, v104
	v_mov_b32_e32 v111, v108
	v_mov_b32_e32 v108, v105
	v_pk_add_f32 v[104:105], v[110:111], v[108:109]
	v_mov_b32_e32 v108, v102
	v_mov_b32_e32 v109, v106
	v_mov_b32_e32 v106, v103
	v_pk_add_f32 v[102:103], v[108:109], v[106:107]
	s_add_u32 s26, s8, s62
	v_pk_add_f32 v[102:103], v[104:105], v[102:103]
	s_addc_u32 s27, s9, s63
	v_add_f32_e32 v104, v102, v103
	v_lshl_add_u64 v[102:103], s[26:27], 0, v[100:101]
	v_lshl_add_u64 v[102:103], v[102:103], 0, v[220:221]
	v_cvt_pk_bf16_f32 v106, v60, v61
	v_cvt_pk_bf16_f32 v107, v62, v63
	v_cvt_pk_bf16_f32 v108, v56, v57
	v_cvt_pk_bf16_f32 v109, v58, v59
	global_store_dwordx4 v[102:103], v[106:109], off
	s_mov_b64 s[28:29], 0

.LBB0_610:
	s_waitcnt vmcnt(6)
	s_nop 0
	v_lshlrev_b32_e32 v56, 16, v198
	v_and_b32_e32 v57, 0xffff0000, v198
	v_lshlrev_b32_e32 v58, 16, v199
	v_and_b32_e32 v59, 0xffff0000, v199
	v_lshlrev_b32_e32 v60, 16, v200
	v_and_b32_e32 v61, 0xffff0000, v200
	v_lshlrev_b32_e32 v62, 16, v201
	v_and_b32_e32 v63, 0xffff0000, v201
	v_pk_add_f32 v[54:55], v[54:55], v[58:59]
	v_pk_add_f32 v[52:53], v[52:53], v[56:57]
	v_pk_add_f32 v[50:51], v[50:51], v[62:63]
	v_pk_add_f32 v[48:49], v[48:49], v[60:61]
	s_mov_b64 s[28:29], -1
	s_and_b64 vcc, exec, s[44:45]
	s_cbranch_vccnz .LBB0_613
	s_andn2_b64 vcc, exec, s[28:29]
	s_cbranch_vccz .LBB0_614

.LBB0_618:
	s_waitcnt vmcnt(5)
	v_lshlrev_b32_e32 v50, 16, v202
	v_and_b32_e32 v51, 0xffff0000, v202
	v_lshlrev_b32_e32 v52, 16, v203
	v_and_b32_e32 v53, 0xffff0000, v203
	v_lshlrev_b32_e32 v54, 16, v204
	v_and_b32_e32 v55, 0xffff0000, v204
	v_lshlrev_b32_e32 v56, 16, v205
	v_and_b32_e32 v57, 0xffff0000, v205
	s_waitcnt lgkmcnt(0)
	v_lshlrev_b64 v[48:49], 7, v[96:97]
	v_pk_add_f32 v[46:47], v[46:47], v[52:53]
	v_pk_add_f32 v[44:45], v[44:45], v[50:51]
	v_pk_add_f32 v[42:43], v[42:43], v[56:57]
	v_pk_add_f32 v[40:41], v[40:41], v[54:55]
	s_mov_b64 s[28:29], -1
	s_and_b64 vcc, exec, s[44:45]
	s_cbranch_vccz .LBB0_620
	v_pk_mul_f32 v[52:53], v[44:45], v[44:45]
	v_pk_mul_f32 v[56:57], v[40:41], v[40:41]
	v_pk_mul_f32 v[50:51], v[46:47], v[46:47]
	v_pk_mul_f32 v[54:55], v[42:43], v[42:43]
	v_mov_b32_e32 v58, v52
	v_mov_b32_e32 v59, v56
	v_mov_b32_e32 v56, v53
	v_pk_add_f32 v[52:53], v[58:59], v[56:57]
	v_mov_b32_e32 v56, v50
	v_mov_b32_e32 v57, v54
	v_mov_b32_e32 v54, v51
	v_pk_add_f32 v[50:51], v[56:57], v[54:55]
	s_add_u32 s26, s8, s62
	v_pk_add_f32 v[50:51], v[52:53], v[50:51]
	s_addc_u32 s27, s9, s63
	v_add_f32_e32 v52, v50, v51
	v_lshl_add_u64 v[50:51], s[26:27], 0, v[48:49]
	v_lshl_add_u64 v[50:51], v[50:51], 0, v[220:221]
	v_cvt_pk_bf16_f32 v54, v44, v45
	v_cvt_pk_bf16_f32 v55, v46, v47
	v_cvt_pk_bf16_f32 v56, v40, v41
	v_cvt_pk_bf16_f32 v57, v42, v43
	global_store_dwordx4 v[50:51], v[54:57], off
	s_mov_b64 s[28:29], 0

.LBB0_622:
	s_waitcnt vmcnt(4)
	s_nop 0
	v_lshlrev_b32_e32 v40, 16, v206
	v_and_b32_e32 v41, 0xffff0000, v206
	v_lshlrev_b32_e32 v42, 16, v207
	v_and_b32_e32 v43, 0xffff0000, v207
	v_lshlrev_b32_e32 v44, 16, v208
	v_and_b32_e32 v45, 0xffff0000, v208
	v_lshlrev_b32_e32 v46, 16, v209
	v_and_b32_e32 v47, 0xffff0000, v209
	v_pk_add_f32 v[38:39], v[38:39], v[42:43]
	v_pk_add_f32 v[36:37], v[36:37], v[40:41]
	v_pk_add_f32 v[34:35], v[34:35], v[46:47]
	v_pk_add_f32 v[32:33], v[32:33], v[44:45]
	s_mov_b64 s[28:29], -1
	s_and_b64 vcc, exec, s[44:45]
	s_cbranch_vccnz .LBB0_625
	s_andn2_b64 vcc, exec, s[28:29]
	s_cbranch_vccz .LBB0_626

.LBB0_630:
	s_waitcnt vmcnt(3)
	v_lshlrev_b32_e32 v34, 16, v210
	v_and_b32_e32 v35, 0xffff0000, v210
	v_lshlrev_b32_e32 v36, 16, v211
	v_and_b32_e32 v37, 0xffff0000, v211
	v_lshlrev_b32_e32 v38, 16, v212
	v_and_b32_e32 v39, 0xffff0000, v212
	v_lshlrev_b32_e32 v40, 16, v213
	v_and_b32_e32 v41, 0xffff0000, v213
	s_waitcnt lgkmcnt(0)
	v_lshlrev_b64 v[32:33], 7, v[94:95]
	v_pk_add_f32 v[30:31], v[30:31], v[36:37]
	v_pk_add_f32 v[28:29], v[28:29], v[34:35]
	v_pk_add_f32 v[26:27], v[26:27], v[40:41]
	v_pk_add_f32 v[24:25], v[24:25], v[38:39]
	s_mov_b64 s[28:29], -1
	s_and_b64 vcc, exec, s[44:45]
	s_cbranch_vccz .LBB0_632
	v_pk_mul_f32 v[36:37], v[28:29], v[28:29]
	v_pk_mul_f32 v[40:41], v[24:25], v[24:25]
	v_pk_mul_f32 v[34:35], v[30:31], v[30:31]
	v_pk_mul_f32 v[38:39], v[26:27], v[26:27]
	v_mov_b32_e32 v42, v36
	v_mov_b32_e32 v43, v40
	v_mov_b32_e32 v40, v37
	v_pk_add_f32 v[36:37], v[42:43], v[40:41]
	v_mov_b32_e32 v40, v34
	v_mov_b32_e32 v41, v38
	v_mov_b32_e32 v38, v35
	v_pk_add_f32 v[34:35], v[40:41], v[38:39]
	s_add_u32 s26, s8, s62
	v_pk_add_f32 v[34:35], v[36:37], v[34:35]
	s_addc_u32 s27, s9, s63
	v_add_f32_e32 v36, v34, v35
	v_lshl_add_u64 v[34:35], s[26:27], 0, v[32:33]
	v_lshl_add_u64 v[34:35], v[34:35], 0, v[220:221]
	v_cvt_pk_bf16_f32 v38, v28, v29
	v_cvt_pk_bf16_f32 v39, v30, v31
	v_cvt_pk_bf16_f32 v40, v24, v25
	v_cvt_pk_bf16_f32 v41, v26, v27
	global_store_dwordx4 v[34:35], v[38:41], off
	s_mov_b64 s[28:29], 0
